# fp8 gate epilogue rewritten by hand: one scale multiply per element (rs*-log2e folded per row), 256*rcp(1+e) as rcp(fma(e,2^-8,2^-8)), byte packing with SDWA byte writes
# speedup vs baseline: 1.0308x; 1.0097x over previous
; __device__ __forceinline__ float sigmoidf_(float x) { return frcp(1.0f + fexp2(-x * LOG2E)); }
;   __device__ __forceinline__ void epilogue(int u, f32x4 (&acc)[2][2][4][2]) const {
;     int pm, pn; tile(u, pm, pn);
;     const float* ssq = p->ssq_x + (long)l * NTOK + c * CT + pm * 256;
;     char* grow = (char*)(p->proj + (long)pm * 256 * INW) + 2 * C_MRG + pn * 256;
;     const int t_ = otid(), w_ = t_ >> 6, l_ = t_ & 63, wr = w_ >> 2, wc = w_ & 3, fr = l_ & 15, fq = l_ >> 4;
;     float k256 = 256.f, k255 = 255.f; asm volatile("" : "+v"(k256), "+v"(k255));
; #pragma unroll
;     for (int ai = 0; ai < 2; ++ai)
; #pragma unroll
;       for (int m = 0; m < 4; ++m) {
;         const unsigned r = ai * 128 + wr * 64 + m * 16 + fr;
;         const float rs = rsqrtf(ssq[r] * (1.0f / DM) + EPS) * (1.0f / 32.0f);
; #pragma unroll
;         for (int bj = 0; bj < 2; ++bj) {
;           uint2 gq;
; #pragma unroll
;           for (int n = 0; n < 2; ++n) {
;             const f32x4 v = acc[ai][bj][m][n];
;             const unsigned q0 = (unsigned)fminf(sigmoidf_(v[0] * rs) * k256, k255), q1 = (unsigned)fminf(sigmoidf_(v[1] * rs) * k256, k255);
;             const unsigned q2 = (unsigned)fminf(sigmoidf_(v[2] * rs) * k256, k255), q3 = (unsigned)fminf(sigmoidf_(v[3] * rs) * k256, k255);
;             const unsigned w = q0 | (q1 << 8) | (q2 << 16) | (q3 << 24);
;             if (n == 0) gq.x = w; else gq.y = w;
;           }
;           *(uint2*)(grow + (r * (unsigned)(INW * 2) + (unsigned)(bj * 128 + wc * 32 + fq * 8))) = gq;
;         }
;       }
;   }
.LBB0_341:
	s_or_b64 exec, exec, s[4:5]
	v_mov_b32_e32 v156, 0x3b800000
	s_lshl_b32 s4, s71, 8
	v_readlane_b32 s5, v254, 0
	s_add_i32 s40, s4, s5
	s_cmp_gt_u32 s71, 1
	v_readlane_b32 s46, v255, 10
	s_cselect_b64 s[4:5], -1, 0
	v_readlane_b32 s47, v255, 11
	s_and_b64 s[4:5], s[46:47], s[4:5]
	s_cmp_eq_u32 s71, 3
	s_movk_i32 s41, 0x2c0
	s_cselect_b32 s41, s41, 0x380
	s_cmp_lg_u32 s71, 2
	s_cselect_b32 s41, s41, 0x200
	v_readlane_b32 s46, v255, 42
	s_add_i32 s41, s41, s46
	s_and_b64 s[4:5], s[4:5], exec
	s_cselect_b32 s4, s41, s40
	s_ashr_i32 s5, s4, 31
	s_lshr_b32 s5, s5, 29
	s_add_i32 s5, s4, s5
	s_ashr_i32 s40, s5, 3
	s_and_b32 s5, s5, -8
	s_sub_i32 s4, s4, s5
	s_lshr_b32 s5, s4, 31
	s_bitset1_b32 s5, 7
	s_mul_i32 s4, s5, s4
	s_add_i32 s4, s4, s40
	s_ashr_i32 s5, s4, 31
	s_lshr_b32 s5, s5, 25
	s_add_i32 s5, s4, s5
	s_ashr_i32 s40, s5, 7
	s_lshl_b32 s40, s40, 3
	s_sub_i32 s41, 64, s40
	s_min_i32 s41, s41, 8
	s_abs_i32 s46, s41
	v_cvt_f32_u32_e32 v0, s46
	s_sub_i32 s48, 0, s46
	s_and_b32 s5, s5, 0xffffff80
	s_sub_i32 s4, s4, s5
	v_rcp_iflag_f32_e32 v0, v0
	s_abs_i32 s5, s4
	s_xor_b32 s47, s4, s41
	s_ashr_i32 s47, s47, 31
	v_mul_f32_e32 v0, 0x4f7ffffe, v0
	v_cvt_u32_f32_e32 v0, v0
	s_load_dwordx4 s[80:83], s[0:1], 0xe0
	v_mov_b32_e32 v144, 0x43800000
	v_mov_b32_e32 v135, 0x437f0000
	v_readfirstlane_b32 s49, v0
	s_mul_i32 s48, s48, s49
	s_mul_hi_u32 s48, s49, s48
	s_add_i32 s49, s49, s48
	s_mul_hi_u32 s48, s5, s49
	s_mul_i32 s49, s48, s46
	s_sub_i32 s5, s5, s49
	s_add_i32 s50, s48, 1
	s_sub_i32 s49, s5, s46
	s_cmp_ge_u32 s5, s46
	s_cselect_b32 s48, s50, s48
	s_cselect_b32 s5, s49, s5
	s_add_i32 s49, s48, 1
	s_cmp_ge_u32 s5, s46
	s_cselect_b32 s5, s49, s48
	s_xor_b32 s5, s5, s47
	s_sub_i32 s46, s5, s47
	s_mul_i32 s5, s46, s41
	s_sub_i32 s4, s4, s5
	s_add_i32 s40, s4, s40
	s_waitcnt lgkmcnt(0)
	s_add_u32 s41, s82, s69
	s_addc_u32 s47, s83, 0
	s_lshl_b64 s[4:5], s[10:11], 2
	s_add_u32 s41, s41, s4
	s_addc_u32 s47, s47, s5
	s_lshl_b32 s4, s40, 8
	s_ashr_i32 s5, s4, 31
	s_lshl_b64 s[4:5], s[4:5], 2
	s_add_u32 s48, s41, s4
	s_addc_u32 s49, s47, s5
	s_mul_hi_i32 s4, s40, 0x4a0000
	s_mul_i32 s40, s40, 0x4a0000
	s_add_u32 s5, s80, s40
	s_addc_u32 s4, s81, s4
	s_lshl_b32 s40, s46, 8
	s_ashr_i32 s41, s40, 31
	s_add_u32 s5, s5, s40
	s_addc_u32 s4, s4, s41
	s_add_u32 s46, s5, 0x2a00
	s_addc_u32 s47, s4, 0
	s_getreg_b32 s4, hwreg(HW_REG_HW_ID, 0, 6)
	s_lshl_b32 s4, s4, 2
	s_and_b32 s4, s4, 0xfc
	s_add_i32 s4, s4, 0
	s_add_i32 s4, s4, 0x21c00
	v_mov_b32_e32 v0, s4
	ds_read_b32 v0, v0
	s_mov_b32 s4, -1
	v_mov_b32_e32 v242, 0x358637bd
	v_mbcnt_lo_u32_b32 v134, s4, 0
	v_mbcnt_hi_u32_b32 v134, s4, v134
	s_waitcnt lgkmcnt(0)
	v_lshl_add_u32 v134, v0, 6, v134
	s_movk_i32 s4, 0xffc0
	v_and_b32_e32 v0, 15, v134
	v_ashrrev_i32_e32 v136, 2, v134
	v_and_or_b32 v0, v136, s4, v0
	v_lshl_add_u64 v[140:141], v[0:1], 2, s[48:49]
	global_load_dword v148, v[140:141], off
	global_load_dword v149, v[140:141], off offset:64
	global_load_dword v150, v[140:141], off offset:128
	global_load_dword v151, v[140:141], off offset:192
	global_load_dword v152, v[140:141], off offset:512
	global_load_dword v153, v[140:141], off offset:576
	global_load_dword v154, v[140:141], off offset:640
	global_load_dword v155, v[140:141], off offset:704
	s_mov_b32 s5, 0x800000
	v_lshrrev_b32_e32 v134, 1, v134
	v_max_f32_e32 v145, v135, v135
	v_mul_lo_u32 v135, v0, s91
	s_movk_i32 s4, 0x78
	v_and_or_b32 v146, v134, s4, v135
	v_readlane_b32 s4, v255, 12
	s_mov_b32 s79, 0x800000
	s_cmp_eq_u32 s70, s4
	s_mov_b32 s71, s70
	v_mov_b32_e32 v243, 0xf149f2ca
	s_waitcnt vmcnt(0)
	v_fmamk_f32 v157, v148, 0x3a800000, v242
	v_mul_f32_e32 v158, 0x4b800000, v157
	v_cmp_gt_f32_e64 s[40:41], s5, v157
	s_nop 1
	v_cndmask_b32_e64 v157, v157, v158, s[40:41]
	v_rsq_f32_e32 v157, v157
	s_nop 0
	v_mul_f32_e32 v158, 0x45800000, v157
	v_cndmask_b32_e64 v157, v157, v158, s[40:41]
	v_mul_f32_e32 v157, 0x3d000000, v157
	v_mul_f32_e32 v157, 0xbfb8aa3b, v157
	v_mul_f32_e32 v126, v126, v157
	v_mul_f32_e32 v127, v127, v157
	v_mul_f32_e32 v128, v128, v157
	v_mul_f32_e32 v129, v129, v157
	v_mul_f32_e32 v122, v122, v157
	v_mul_f32_e32 v123, v123, v157
	v_mul_f32_e32 v124, v124, v157
	v_mul_f32_e32 v125, v125, v157
	v_mul_f32_e32 v118, v118, v157
	v_mul_f32_e32 v119, v119, v157
	v_mul_f32_e32 v120, v120, v157
	v_mul_f32_e32 v121, v121, v157
	v_mul_f32_e32 v114, v114, v157
	v_mul_f32_e32 v115, v115, v157
	v_mul_f32_e32 v116, v116, v157
	v_mul_f32_e32 v117, v117, v157
	v_exp_f32_e32 v126, v126
	v_exp_f32_e32 v127, v127
	v_exp_f32_e32 v128, v128
	v_exp_f32_e32 v129, v129
	v_exp_f32_e32 v122, v122
	v_exp_f32_e32 v123, v123
	v_exp_f32_e32 v124, v124
	v_exp_f32_e32 v125, v125
	v_exp_f32_e32 v118, v118
	v_exp_f32_e32 v119, v119
	v_exp_f32_e32 v120, v120
	v_exp_f32_e32 v121, v121
	v_exp_f32_e32 v114, v114
	v_exp_f32_e32 v115, v115
	v_exp_f32_e32 v116, v116
	v_exp_f32_e32 v117, v117
	v_fmamk_f32 v126, v126, 0x3b800000, v156
	v_fmamk_f32 v127, v127, 0x3b800000, v156
	v_fmamk_f32 v128, v128, 0x3b800000, v156
	v_fmamk_f32 v129, v129, 0x3b800000, v156
	v_fmamk_f32 v122, v122, 0x3b800000, v156
	v_fmamk_f32 v123, v123, 0x3b800000, v156
	v_fmamk_f32 v124, v124, 0x3b800000, v156
	v_fmamk_f32 v125, v125, 0x3b800000, v156
	v_fmamk_f32 v118, v118, 0x3b800000, v156
	v_fmamk_f32 v119, v119, 0x3b800000, v156
	v_fmamk_f32 v120, v120, 0x3b800000, v156
	v_fmamk_f32 v121, v121, 0x3b800000, v156
	v_fmamk_f32 v114, v114, 0x3b800000, v156
	v_fmamk_f32 v115, v115, 0x3b800000, v156
	v_fmamk_f32 v116, v116, 0x3b800000, v156
	v_fmamk_f32 v117, v117, 0x3b800000, v156
	v_rcp_f32_e32 v126, v126
	v_rcp_f32_e32 v127, v127
	v_rcp_f32_e32 v128, v128
	v_rcp_f32_e32 v129, v129
; __device__ __forceinline__ float sigmoidf_(float x) { return frcp(1.0f + fexp2(-x * LOG2E)); }
;   __device__ __forceinline__ void epilogue(int u, f32x4 (&acc)[2][2][4][2]) const {
;     int pm, pn; tile(u, pm, pn);
;     const float* ssq = p->ssq_x + (long)l * NTOK + c * CT + pm * 256;
;     char* grow = (char*)(p->proj + (long)pm * 256 * INW) + 2 * C_MRG + pn * 256;
;     const int t_ = otid(), w_ = t_ >> 6, l_ = t_ & 63, wr = w_ >> 2, wc = w_ & 3, fr = l_ & 15, fq = l_ >> 4;
;     float k256 = 256.f, k255 = 255.f; asm volatile("" : "+v"(k256), "+v"(k255));
; #pragma unroll
;     for (int ai = 0; ai < 2; ++ai)
; #pragma unroll
;       for (int m = 0; m < 4; ++m) {
;         const unsigned r = ai * 128 + wr * 64 + m * 16 + fr;
;         const float rs = rsqrtf(ssq[r] * (1.0f / DM) + EPS) * (1.0f / 32.0f);
; #pragma unroll
;         for (int bj = 0; bj < 2; ++bj) {
;           uint2 gq;
; #pragma unroll
;           for (int n = 0; n < 2; ++n) {
;             const f32x4 v = acc[ai][bj][m][n];
;             const unsigned q0 = (unsigned)fminf(sigmoidf_(v[0] * rs) * k256, k255), q1 = (unsigned)fminf(sigmoidf_(v[1] * rs) * k256, k255);
;             const unsigned q2 = (unsigned)fminf(sigmoidf_(v[2] * rs) * k256, k255), q3 = (unsigned)fminf(sigmoidf_(v[3] * rs) * k256, k255);
;             const unsigned w = q0 | (q1 << 8) | (q2 << 16) | (q3 << 24);
;             if (n == 0) gq.x = w; else gq.y = w;
;           }
;           *(uint2*)(grow + (r * (unsigned)(INW * 2) + (unsigned)(bj * 128 + wc * 32 + fq * 8))) = gq;
;         }
;       }
;   }
	v_rcp_f32_e32 v122, v122
	v_rcp_f32_e32 v123, v123
	v_rcp_f32_e32 v124, v124
	v_rcp_f32_e32 v125, v125
	v_rcp_f32_e32 v118, v118
	v_rcp_f32_e32 v119, v119
	v_rcp_f32_e32 v120, v120
	v_rcp_f32_e32 v121, v121
	v_rcp_f32_e32 v114, v114
	v_rcp_f32_e32 v115, v115
	v_rcp_f32_e32 v116, v116
	v_rcp_f32_e32 v117, v117
	v_min_f32_e32 v126, v126, v145
	v_min_f32_e32 v127, v127, v145
	v_min_f32_e32 v128, v128, v145
	v_min_f32_e32 v129, v129, v145
	v_min_f32_e32 v122, v122, v145
	v_min_f32_e32 v123, v123, v145
	v_min_f32_e32 v124, v124, v145
	v_min_f32_e32 v125, v125, v145
	v_min_f32_e32 v118, v118, v145
	v_min_f32_e32 v119, v119, v145
	v_min_f32_e32 v120, v120, v145
	v_min_f32_e32 v121, v121, v145
	v_min_f32_e32 v114, v114, v145
	v_min_f32_e32 v115, v115, v145
	v_min_f32_e32 v116, v116, v145
	v_min_f32_e32 v117, v117, v145
	v_cvt_u32_f32_e32 v160, v126
	v_cvt_u32_f32_e32 v161, v122
	v_cvt_u32_f32_e32 v162, v118
	v_cvt_u32_f32_e32 v163, v114
	v_cvt_u32_f32_sdwa v160, v127 dst_sel:BYTE_1 dst_unused:UNUSED_PRESERVE src0_sel:DWORD
	v_cvt_u32_f32_sdwa v161, v123 dst_sel:BYTE_1 dst_unused:UNUSED_PRESERVE src0_sel:DWORD
	v_cvt_u32_f32_sdwa v162, v119 dst_sel:BYTE_1 dst_unused:UNUSED_PRESERVE src0_sel:DWORD
	v_cvt_u32_f32_sdwa v163, v115 dst_sel:BYTE_1 dst_unused:UNUSED_PRESERVE src0_sel:DWORD
	v_cvt_u32_f32_sdwa v160, v128 dst_sel:BYTE_2 dst_unused:UNUSED_PRESERVE src0_sel:DWORD
	v_cvt_u32_f32_sdwa v161, v124 dst_sel:BYTE_2 dst_unused:UNUSED_PRESERVE src0_sel:DWORD
	v_cvt_u32_f32_sdwa v162, v120 dst_sel:BYTE_2 dst_unused:UNUSED_PRESERVE src0_sel:DWORD
	v_cvt_u32_f32_sdwa v163, v116 dst_sel:BYTE_2 dst_unused:UNUSED_PRESERVE src0_sel:DWORD
	v_cvt_u32_f32_sdwa v160, v129 dst_sel:BYTE_3 dst_unused:UNUSED_PRESERVE src0_sel:DWORD
	v_cvt_u32_f32_sdwa v161, v125 dst_sel:BYTE_3 dst_unused:UNUSED_PRESERVE src0_sel:DWORD
	v_cvt_u32_f32_sdwa v162, v121 dst_sel:BYTE_3 dst_unused:UNUSED_PRESERVE src0_sel:DWORD
	v_cvt_u32_f32_sdwa v163, v117 dst_sel:BYTE_3 dst_unused:UNUSED_PRESERVE src0_sel:DWORD
	s_nop 1
	global_store_dwordx2 v146, v[160:161], s[46:47]
	global_store_dwordx2 v146, v[162:163], s[46:47] offset:128
	v_fmamk_f32 v157, v149, 0x3a800000, v242
	v_mul_f32_e32 v158, 0x4b800000, v157
	v_cmp_gt_f32_e64 s[40:41], s5, v157
	s_nop 1
	v_cndmask_b32_e64 v157, v157, v158, s[40:41]
	v_rsq_f32_e32 v157, v157
	s_nop 0
	v_mul_f32_e32 v158, 0x45800000, v157
	v_cndmask_b32_e64 v157, v157, v158, s[40:41]
	v_mul_f32_e32 v157, 0x3d000000, v157
	v_mul_f32_e32 v157, 0xbfb8aa3b, v157
	v_mul_f32_e32 v110, v110, v157
	v_mul_f32_e32 v111, v111, v157
	v_mul_f32_e32 v112, v112, v157
	v_mul_f32_e32 v113, v113, v157
	v_mul_f32_e32 v106, v106, v157
	v_mul_f32_e32 v107, v107, v157
	v_mul_f32_e32 v108, v108, v157
	v_mul_f32_e32 v109, v109, v157
	v_mul_f32_e32 v102, v102, v157
	v_mul_f32_e32 v103, v103, v157
	v_mul_f32_e32 v104, v104, v157
	v_mul_f32_e32 v105, v105, v157
	v_mul_f32_e32 v98, v98, v157
	v_mul_f32_e32 v99, v99, v157
	v_mul_f32_e32 v100, v100, v157
	v_mul_f32_e32 v101, v101, v157
	v_exp_f32_e32 v110, v110
	v_exp_f32_e32 v111, v111
	v_exp_f32_e32 v112, v112
	v_exp_f32_e32 v113, v113
	v_exp_f32_e32 v106, v106
	v_exp_f32_e32 v107, v107
	v_exp_f32_e32 v108, v108
	v_exp_f32_e32 v109, v109
	v_exp_f32_e32 v102, v102
	v_exp_f32_e32 v103, v103
	v_exp_f32_e32 v104, v104
	v_exp_f32_e32 v105, v105
	v_exp_f32_e32 v98, v98
	v_exp_f32_e32 v99, v99
	v_exp_f32_e32 v100, v100
	v_exp_f32_e32 v101, v101
	v_fmamk_f32 v110, v110, 0x3b800000, v156
	v_fmamk_f32 v111, v111, 0x3b800000, v156
	v_fmamk_f32 v112, v112, 0x3b800000, v156
	v_fmamk_f32 v113, v113, 0x3b800000, v156
	v_fmamk_f32 v106, v106, 0x3b800000, v156
	v_fmamk_f32 v107, v107, 0x3b800000, v156
	v_fmamk_f32 v108, v108, 0x3b800000, v156
	v_fmamk_f32 v109, v109, 0x3b800000, v156
	v_fmamk_f32 v102, v102, 0x3b800000, v156
	v_fmamk_f32 v103, v103, 0x3b800000, v156
	v_fmamk_f32 v104, v104, 0x3b800000, v156
	v_fmamk_f32 v105, v105, 0x3b800000, v156
	v_fmamk_f32 v98, v98, 0x3b800000, v156
	v_fmamk_f32 v99, v99, 0x3b800000, v156
	v_fmamk_f32 v100, v100, 0x3b800000, v156
	v_fmamk_f32 v101, v101, 0x3b800000, v156
	v_rcp_f32_e32 v110, v110
	v_rcp_f32_e32 v111, v111
	v_rcp_f32_e32 v112, v112
	v_rcp_f32_e32 v113, v113
	v_rcp_f32_e32 v106, v106
	v_rcp_f32_e32 v107, v107
	v_rcp_f32_e32 v108, v108
	v_rcp_f32_e32 v109, v109
	v_rcp_f32_e32 v102, v102
	v_rcp_f32_e32 v103, v103
	v_rcp_f32_e32 v104, v104
	v_rcp_f32_e32 v105, v105
	v_rcp_f32_e32 v98, v98
	v_rcp_f32_e32 v99, v99
	v_rcp_f32_e32 v100, v100
	v_rcp_f32_e32 v101, v101
	v_min_f32_e32 v110, v110, v145
	v_min_f32_e32 v111, v111, v145
	v_min_f32_e32 v112, v112, v145
	v_min_f32_e32 v113, v113, v145
	v_min_f32_e32 v106, v106, v145
	v_min_f32_e32 v107, v107, v145
	v_min_f32_e32 v108, v108, v145
	v_min_f32_e32 v109, v109, v145
	v_min_f32_e32 v102, v102, v145
	v_min_f32_e32 v103, v103, v145
	v_min_f32_e32 v104, v104, v145
	v_min_f32_e32 v105, v105, v145
	v_min_f32_e32 v98, v98, v145
	v_min_f32_e32 v99, v99, v145
	v_min_f32_e32 v100, v100, v145
	v_min_f32_e32 v101, v101, v145
	v_add_u32_e32 v193, 0x4a000, v146
	v_cvt_u32_f32_e32 v164, v110
	v_cvt_u32_f32_e32 v165, v106
	v_cvt_u32_f32_e32 v166, v102
	v_cvt_u32_f32_e32 v167, v98
	v_cvt_u32_f32_sdwa v164, v111 dst_sel:BYTE_1 dst_unused:UNUSED_PRESERVE src0_sel:DWORD
	v_cvt_u32_f32_sdwa v165, v107 dst_sel:BYTE_1 dst_unused:UNUSED_PRESERVE src0_sel:DWORD
	v_cvt_u32_f32_sdwa v166, v103 dst_sel:BYTE_1 dst_unused:UNUSED_PRESERVE src0_sel:DWORD
	v_cvt_u32_f32_sdwa v167, v99 dst_sel:BYTE_1 dst_unused:UNUSED_PRESERVE src0_sel:DWORD
	v_cvt_u32_f32_sdwa v164, v112 dst_sel:BYTE_2 dst_unused:UNUSED_PRESERVE src0_sel:DWORD
	v_cvt_u32_f32_sdwa v165, v108 dst_sel:BYTE_2 dst_unused:UNUSED_PRESERVE src0_sel:DWORD
; __device__ __forceinline__ float sigmoidf_(float x) { return frcp(1.0f + fexp2(-x * LOG2E)); }
;   __device__ __forceinline__ void epilogue(int u, f32x4 (&acc)[2][2][4][2]) const {
;     int pm, pn; tile(u, pm, pn);
;     const float* ssq = p->ssq_x + (long)l * NTOK + c * CT + pm * 256;
;     char* grow = (char*)(p->proj + (long)pm * 256 * INW) + 2 * C_MRG + pn * 256;
;     const int t_ = otid(), w_ = t_ >> 6, l_ = t_ & 63, wr = w_ >> 2, wc = w_ & 3, fr = l_ & 15, fq = l_ >> 4;
;     float k256 = 256.f, k255 = 255.f; asm volatile("" : "+v"(k256), "+v"(k255));
; #pragma unroll
;     for (int ai = 0; ai < 2; ++ai)
; #pragma unroll
;       for (int m = 0; m < 4; ++m) {
;         const unsigned r = ai * 128 + wr * 64 + m * 16 + fr;
;         const float rs = rsqrtf(ssq[r] * (1.0f / DM) + EPS) * (1.0f / 32.0f);
; #pragma unroll
;         for (int bj = 0; bj < 2; ++bj) {
;           uint2 gq;
; #pragma unroll
;           for (int n = 0; n < 2; ++n) {
;             const f32x4 v = acc[ai][bj][m][n];
;             const unsigned q0 = (unsigned)fminf(sigmoidf_(v[0] * rs) * k256, k255), q1 = (unsigned)fminf(sigmoidf_(v[1] * rs) * k256, k255);
;             const unsigned q2 = (unsigned)fminf(sigmoidf_(v[2] * rs) * k256, k255), q3 = (unsigned)fminf(sigmoidf_(v[3] * rs) * k256, k255);
;             const unsigned w = q0 | (q1 << 8) | (q2 << 16) | (q3 << 24);
;             if (n == 0) gq.x = w; else gq.y = w;
;           }
;           *(uint2*)(grow + (r * (unsigned)(INW * 2) + (unsigned)(bj * 128 + wc * 32 + fq * 8))) = gq;
;         }
;       }
;   }
	v_cvt_u32_f32_sdwa v166, v104 dst_sel:BYTE_2 dst_unused:UNUSED_PRESERVE src0_sel:DWORD
	v_cvt_u32_f32_sdwa v167, v100 dst_sel:BYTE_2 dst_unused:UNUSED_PRESERVE src0_sel:DWORD
	v_cvt_u32_f32_sdwa v164, v113 dst_sel:BYTE_3 dst_unused:UNUSED_PRESERVE src0_sel:DWORD
	v_cvt_u32_f32_sdwa v165, v109 dst_sel:BYTE_3 dst_unused:UNUSED_PRESERVE src0_sel:DWORD
	v_cvt_u32_f32_sdwa v166, v105 dst_sel:BYTE_3 dst_unused:UNUSED_PRESERVE src0_sel:DWORD
	v_cvt_u32_f32_sdwa v167, v101 dst_sel:BYTE_3 dst_unused:UNUSED_PRESERVE src0_sel:DWORD
	s_nop 1
	global_store_dwordx2 v193, v[164:165], s[46:47]
	global_store_dwordx2 v193, v[166:167], s[46:47] offset:128
	v_fmamk_f32 v157, v150, 0x3a800000, v242
	v_mul_f32_e32 v158, 0x4b800000, v157
	v_cmp_gt_f32_e64 s[40:41], s5, v157
	s_nop 1
	v_cndmask_b32_e64 v157, v157, v158, s[40:41]
	v_rsq_f32_e32 v157, v157
	s_nop 0
	v_mul_f32_e32 v158, 0x45800000, v157
	v_cndmask_b32_e64 v157, v157, v158, s[40:41]
	v_mul_f32_e32 v157, 0x3d000000, v157
	v_mul_f32_e32 v157, 0xbfb8aa3b, v157
	v_mul_f32_e32 v94, v94, v157
	v_mul_f32_e32 v95, v95, v157
	v_mul_f32_e32 v96, v96, v157
	v_mul_f32_e32 v97, v97, v157
	v_mul_f32_e32 v90, v90, v157
	v_mul_f32_e32 v91, v91, v157
	v_mul_f32_e32 v92, v92, v157
	v_mul_f32_e32 v93, v93, v157
	v_mul_f32_e32 v86, v86, v157
	v_mul_f32_e32 v87, v87, v157
	v_mul_f32_e32 v88, v88, v157
	v_mul_f32_e32 v89, v89, v157
	v_mul_f32_e32 v82, v82, v157
	v_mul_f32_e32 v83, v83, v157
	v_mul_f32_e32 v84, v84, v157
	v_mul_f32_e32 v85, v85, v157
	v_exp_f32_e32 v94, v94
	v_exp_f32_e32 v95, v95
	v_exp_f32_e32 v96, v96
	v_exp_f32_e32 v97, v97
	v_exp_f32_e32 v90, v90
	v_exp_f32_e32 v91, v91
	v_exp_f32_e32 v92, v92
	v_exp_f32_e32 v93, v93
	v_exp_f32_e32 v86, v86
	v_exp_f32_e32 v87, v87
	v_exp_f32_e32 v88, v88
	v_exp_f32_e32 v89, v89
	v_exp_f32_e32 v82, v82
	v_exp_f32_e32 v83, v83
	v_exp_f32_e32 v84, v84
	v_exp_f32_e32 v85, v85
	v_fmamk_f32 v94, v94, 0x3b800000, v156
	v_fmamk_f32 v95, v95, 0x3b800000, v156
	v_fmamk_f32 v96, v96, 0x3b800000, v156
	v_fmamk_f32 v97, v97, 0x3b800000, v156
	v_fmamk_f32 v90, v90, 0x3b800000, v156
	v_fmamk_f32 v91, v91, 0x3b800000, v156
	v_fmamk_f32 v92, v92, 0x3b800000, v156
	v_fmamk_f32 v93, v93, 0x3b800000, v156
	v_fmamk_f32 v86, v86, 0x3b800000, v156
	v_fmamk_f32 v87, v87, 0x3b800000, v156
	v_fmamk_f32 v88, v88, 0x3b800000, v156
	v_fmamk_f32 v89, v89, 0x3b800000, v156
	v_fmamk_f32 v82, v82, 0x3b800000, v156
	v_fmamk_f32 v83, v83, 0x3b800000, v156
	v_fmamk_f32 v84, v84, 0x3b800000, v156
	v_fmamk_f32 v85, v85, 0x3b800000, v156
	v_rcp_f32_e32 v94, v94
	v_rcp_f32_e32 v95, v95
	v_rcp_f32_e32 v96, v96
	v_rcp_f32_e32 v97, v97
	v_rcp_f32_e32 v90, v90
	v_rcp_f32_e32 v91, v91
	v_rcp_f32_e32 v92, v92
	v_rcp_f32_e32 v93, v93
	v_rcp_f32_e32 v86, v86
	v_rcp_f32_e32 v87, v87
	v_rcp_f32_e32 v88, v88
	v_rcp_f32_e32 v89, v89
	v_rcp_f32_e32 v82, v82
	v_rcp_f32_e32 v83, v83
	v_rcp_f32_e32 v84, v84
	v_rcp_f32_e32 v85, v85
	v_min_f32_e32 v94, v94, v145
	v_min_f32_e32 v95, v95, v145
	v_min_f32_e32 v96, v96, v145
	v_min_f32_e32 v97, v97, v145
	v_min_f32_e32 v90, v90, v145
	v_min_f32_e32 v91, v91, v145
	v_min_f32_e32 v92, v92, v145
	v_min_f32_e32 v93, v93, v145
	v_min_f32_e32 v86, v86, v145
	v_min_f32_e32 v87, v87, v145
	v_min_f32_e32 v88, v88, v145
	v_min_f32_e32 v89, v89, v145
	v_min_f32_e32 v82, v82, v145
	v_min_f32_e32 v83, v83, v145
	v_min_f32_e32 v84, v84, v145
	v_min_f32_e32 v85, v85, v145
	v_add_u32_e32 v194, 0x94000, v146
	v_cvt_u32_f32_e32 v168, v94
	v_cvt_u32_f32_e32 v169, v90
	v_cvt_u32_f32_e32 v170, v86
	v_cvt_u32_f32_e32 v171, v82
	v_cvt_u32_f32_sdwa v168, v95 dst_sel:BYTE_1 dst_unused:UNUSED_PRESERVE src0_sel:DWORD
	v_cvt_u32_f32_sdwa v169, v91 dst_sel:BYTE_1 dst_unused:UNUSED_PRESERVE src0_sel:DWORD
	v_cvt_u32_f32_sdwa v170, v87 dst_sel:BYTE_1 dst_unused:UNUSED_PRESERVE src0_sel:DWORD
	v_cvt_u32_f32_sdwa v171, v83 dst_sel:BYTE_1 dst_unused:UNUSED_PRESERVE src0_sel:DWORD
	v_cvt_u32_f32_sdwa v168, v96 dst_sel:BYTE_2 dst_unused:UNUSED_PRESERVE src0_sel:DWORD
	v_cvt_u32_f32_sdwa v169, v92 dst_sel:BYTE_2 dst_unused:UNUSED_PRESERVE src0_sel:DWORD
	v_cvt_u32_f32_sdwa v170, v88 dst_sel:BYTE_2 dst_unused:UNUSED_PRESERVE src0_sel:DWORD
	v_cvt_u32_f32_sdwa v171, v84 dst_sel:BYTE_2 dst_unused:UNUSED_PRESERVE src0_sel:DWORD
	v_cvt_u32_f32_sdwa v168, v97 dst_sel:BYTE_3 dst_unused:UNUSED_PRESERVE src0_sel:DWORD
	v_cvt_u32_f32_sdwa v169, v93 dst_sel:BYTE_3 dst_unused:UNUSED_PRESERVE src0_sel:DWORD
	v_cvt_u32_f32_sdwa v170, v89 dst_sel:BYTE_3 dst_unused:UNUSED_PRESERVE src0_sel:DWORD
	v_cvt_u32_f32_sdwa v171, v85 dst_sel:BYTE_3 dst_unused:UNUSED_PRESERVE src0_sel:DWORD
	s_nop 1
	global_store_dwordx2 v194, v[168:169], s[46:47]
	global_store_dwordx2 v194, v[170:171], s[46:47] offset:128
	v_fmamk_f32 v157, v151, 0x3a800000, v242
	v_mul_f32_e32 v158, 0x4b800000, v157
	v_cmp_gt_f32_e64 s[40:41], s5, v157
	s_nop 1
	v_cndmask_b32_e64 v157, v157, v158, s[40:41]
	v_rsq_f32_e32 v157, v157
	s_nop 0
	v_mul_f32_e32 v158, 0x45800000, v157
	v_cndmask_b32_e64 v157, v157, v158, s[40:41]
	v_mul_f32_e32 v157, 0x3d000000, v157
	v_mul_f32_e32 v157, 0xbfb8aa3b, v157
	v_mul_f32_e32 v70, v70, v157
	v_mul_f32_e32 v71, v71, v157
	v_mul_f32_e32 v72, v72, v157
	v_mul_f32_e32 v73, v73, v157
	v_mul_f32_e32 v66, v66, v157
	v_mul_f32_e32 v67, v67, v157
	v_mul_f32_e32 v68, v68, v157
	v_mul_f32_e32 v69, v69, v157
	v_mul_f32_e32 v78, v78, v157
	v_mul_f32_e32 v79, v79, v157
	v_mul_f32_e32 v80, v80, v157
	v_mul_f32_e32 v81, v81, v157
	v_mul_f32_e32 v74, v74, v157
	v_mul_f32_e32 v75, v75, v157
	v_mul_f32_e32 v76, v76, v157
	v_mul_f32_e32 v77, v77, v157
	v_exp_f32_e32 v70, v70
	v_exp_f32_e32 v71, v71
	v_exp_f32_e32 v72, v72
	v_exp_f32_e32 v73, v73
; __device__ __forceinline__ float sigmoidf_(float x) { return frcp(1.0f + fexp2(-x * LOG2E)); }
;   __device__ __forceinline__ void epilogue(int u, f32x4 (&acc)[2][2][4][2]) const {
;     int pm, pn; tile(u, pm, pn);
;     const float* ssq = p->ssq_x + (long)l * NTOK + c * CT + pm * 256;
;     char* grow = (char*)(p->proj + (long)pm * 256 * INW) + 2 * C_MRG + pn * 256;
;     const int t_ = otid(), w_ = t_ >> 6, l_ = t_ & 63, wr = w_ >> 2, wc = w_ & 3, fr = l_ & 15, fq = l_ >> 4;
;     float k256 = 256.f, k255 = 255.f; asm volatile("" : "+v"(k256), "+v"(k255));
; #pragma unroll
;     for (int ai = 0; ai < 2; ++ai)
; #pragma unroll
;       for (int m = 0; m < 4; ++m) {
;         const unsigned r = ai * 128 + wr * 64 + m * 16 + fr;
;         const float rs = rsqrtf(ssq[r] * (1.0f / DM) + EPS) * (1.0f / 32.0f);
; #pragma unroll
;         for (int bj = 0; bj < 2; ++bj) {
;           uint2 gq;
; #pragma unroll
;           for (int n = 0; n < 2; ++n) {
;             const f32x4 v = acc[ai][bj][m][n];
;             const unsigned q0 = (unsigned)fminf(sigmoidf_(v[0] * rs) * k256, k255), q1 = (unsigned)fminf(sigmoidf_(v[1] * rs) * k256, k255);
;             const unsigned q2 = (unsigned)fminf(sigmoidf_(v[2] * rs) * k256, k255), q3 = (unsigned)fminf(sigmoidf_(v[3] * rs) * k256, k255);
;             const unsigned w = q0 | (q1 << 8) | (q2 << 16) | (q3 << 24);
;             if (n == 0) gq.x = w; else gq.y = w;
;           }
;           *(uint2*)(grow + (r * (unsigned)(INW * 2) + (unsigned)(bj * 128 + wc * 32 + fq * 8))) = gq;
;         }
;       }
;   }
	v_exp_f32_e32 v66, v66
	v_exp_f32_e32 v67, v67
	v_exp_f32_e32 v68, v68
	v_exp_f32_e32 v69, v69
	v_exp_f32_e32 v78, v78
	v_exp_f32_e32 v79, v79
	v_exp_f32_e32 v80, v80
	v_exp_f32_e32 v81, v81
	v_exp_f32_e32 v74, v74
	v_exp_f32_e32 v75, v75
	v_exp_f32_e32 v76, v76
	v_exp_f32_e32 v77, v77
	v_fmamk_f32 v70, v70, 0x3b800000, v156
	v_fmamk_f32 v71, v71, 0x3b800000, v156
	v_fmamk_f32 v72, v72, 0x3b800000, v156
	v_fmamk_f32 v73, v73, 0x3b800000, v156
	v_fmamk_f32 v66, v66, 0x3b800000, v156
	v_fmamk_f32 v67, v67, 0x3b800000, v156
	v_fmamk_f32 v68, v68, 0x3b800000, v156
	v_fmamk_f32 v69, v69, 0x3b800000, v156
	v_fmamk_f32 v78, v78, 0x3b800000, v156
	v_fmamk_f32 v79, v79, 0x3b800000, v156
	v_fmamk_f32 v80, v80, 0x3b800000, v156
	v_fmamk_f32 v81, v81, 0x3b800000, v156
	v_fmamk_f32 v74, v74, 0x3b800000, v156
	v_fmamk_f32 v75, v75, 0x3b800000, v156
	v_fmamk_f32 v76, v76, 0x3b800000, v156
	v_fmamk_f32 v77, v77, 0x3b800000, v156
	v_rcp_f32_e32 v70, v70
	v_rcp_f32_e32 v71, v71
	v_rcp_f32_e32 v72, v72
	v_rcp_f32_e32 v73, v73
	v_rcp_f32_e32 v66, v66
	v_rcp_f32_e32 v67, v67
	v_rcp_f32_e32 v68, v68
	v_rcp_f32_e32 v69, v69
	v_rcp_f32_e32 v78, v78
	v_rcp_f32_e32 v79, v79
	v_rcp_f32_e32 v80, v80
	v_rcp_f32_e32 v81, v81
	v_rcp_f32_e32 v74, v74
	v_rcp_f32_e32 v75, v75
	v_rcp_f32_e32 v76, v76
	v_rcp_f32_e32 v77, v77
	v_min_f32_e32 v70, v70, v145
	v_min_f32_e32 v71, v71, v145
	v_min_f32_e32 v72, v72, v145
	v_min_f32_e32 v73, v73, v145
	v_min_f32_e32 v66, v66, v145
	v_min_f32_e32 v67, v67, v145
	v_min_f32_e32 v68, v68, v145
	v_min_f32_e32 v69, v69, v145
	v_min_f32_e32 v78, v78, v145
	v_min_f32_e32 v79, v79, v145
	v_min_f32_e32 v80, v80, v145
	v_min_f32_e32 v81, v81, v145
	v_min_f32_e32 v74, v74, v145
	v_min_f32_e32 v75, v75, v145
	v_min_f32_e32 v76, v76, v145
	v_min_f32_e32 v77, v77, v145
	v_add_u32_e32 v195, 0xde000, v146
	v_cvt_u32_f32_e32 v172, v70
	v_cvt_u32_f32_e32 v173, v66
	v_cvt_u32_f32_e32 v174, v78
	v_cvt_u32_f32_e32 v175, v74
	v_cvt_u32_f32_sdwa v172, v71 dst_sel:BYTE_1 dst_unused:UNUSED_PRESERVE src0_sel:DWORD
	v_cvt_u32_f32_sdwa v173, v67 dst_sel:BYTE_1 dst_unused:UNUSED_PRESERVE src0_sel:DWORD
	v_cvt_u32_f32_sdwa v174, v79 dst_sel:BYTE_1 dst_unused:UNUSED_PRESERVE src0_sel:DWORD
	v_cvt_u32_f32_sdwa v175, v75 dst_sel:BYTE_1 dst_unused:UNUSED_PRESERVE src0_sel:DWORD
	v_cvt_u32_f32_sdwa v172, v72 dst_sel:BYTE_2 dst_unused:UNUSED_PRESERVE src0_sel:DWORD
	v_cvt_u32_f32_sdwa v173, v68 dst_sel:BYTE_2 dst_unused:UNUSED_PRESERVE src0_sel:DWORD
	v_cvt_u32_f32_sdwa v174, v80 dst_sel:BYTE_2 dst_unused:UNUSED_PRESERVE src0_sel:DWORD
	v_cvt_u32_f32_sdwa v175, v76 dst_sel:BYTE_2 dst_unused:UNUSED_PRESERVE src0_sel:DWORD
	v_cvt_u32_f32_sdwa v172, v73 dst_sel:BYTE_3 dst_unused:UNUSED_PRESERVE src0_sel:DWORD
	v_cvt_u32_f32_sdwa v173, v69 dst_sel:BYTE_3 dst_unused:UNUSED_PRESERVE src0_sel:DWORD
	v_cvt_u32_f32_sdwa v174, v81 dst_sel:BYTE_3 dst_unused:UNUSED_PRESERVE src0_sel:DWORD
	v_cvt_u32_f32_sdwa v175, v77 dst_sel:BYTE_3 dst_unused:UNUSED_PRESERVE src0_sel:DWORD
	s_nop 1
	global_store_dwordx2 v195, v[172:173], s[46:47] offset:128
	global_store_dwordx2 v195, v[174:175], s[46:47]
	v_fmamk_f32 v157, v152, 0x3a800000, v242
	v_mul_f32_e32 v158, 0x4b800000, v157
	v_cmp_gt_f32_e64 s[40:41], s5, v157
	s_nop 1
	v_cndmask_b32_e64 v157, v157, v158, s[40:41]
	v_rsq_f32_e32 v157, v157
	s_nop 0
	v_mul_f32_e32 v158, 0x45800000, v157
	v_cndmask_b32_e64 v157, v157, v158, s[40:41]
	v_mul_f32_e32 v157, 0x3d000000, v157
	v_mul_f32_e32 v157, 0xbfb8aa3b, v157
	v_mul_f32_e32 v54, v54, v157
	v_mul_f32_e32 v55, v55, v157
	v_mul_f32_e32 v56, v56, v157
	v_mul_f32_e32 v57, v57, v157
	v_mul_f32_e32 v50, v50, v157
	v_mul_f32_e32 v51, v51, v157
	v_mul_f32_e32 v52, v52, v157
	v_mul_f32_e32 v53, v53, v157
	v_mul_f32_e32 v62, v62, v157
	v_mul_f32_e32 v63, v63, v157
	v_mul_f32_e32 v64, v64, v157
	v_mul_f32_e32 v65, v65, v157
	v_mul_f32_e32 v58, v58, v157
	v_mul_f32_e32 v59, v59, v157
	v_mul_f32_e32 v60, v60, v157
	v_mul_f32_e32 v61, v61, v157
	v_exp_f32_e32 v54, v54
	v_exp_f32_e32 v55, v55
	v_exp_f32_e32 v56, v56
	v_exp_f32_e32 v57, v57
	v_exp_f32_e32 v50, v50
	v_exp_f32_e32 v51, v51
	v_exp_f32_e32 v52, v52
	v_exp_f32_e32 v53, v53
	v_exp_f32_e32 v62, v62
	v_exp_f32_e32 v63, v63
	v_exp_f32_e32 v64, v64
	v_exp_f32_e32 v65, v65
	v_exp_f32_e32 v58, v58
	v_exp_f32_e32 v59, v59
	v_exp_f32_e32 v60, v60
	v_exp_f32_e32 v61, v61
	v_fmamk_f32 v54, v54, 0x3b800000, v156
	v_fmamk_f32 v55, v55, 0x3b800000, v156
	v_fmamk_f32 v56, v56, 0x3b800000, v156
	v_fmamk_f32 v57, v57, 0x3b800000, v156
	v_fmamk_f32 v50, v50, 0x3b800000, v156
	v_fmamk_f32 v51, v51, 0x3b800000, v156
	v_fmamk_f32 v52, v52, 0x3b800000, v156
	v_fmamk_f32 v53, v53, 0x3b800000, v156
	v_fmamk_f32 v62, v62, 0x3b800000, v156
	v_fmamk_f32 v63, v63, 0x3b800000, v156
	v_fmamk_f32 v64, v64, 0x3b800000, v156
	v_fmamk_f32 v65, v65, 0x3b800000, v156
	v_fmamk_f32 v58, v58, 0x3b800000, v156
	v_fmamk_f32 v59, v59, 0x3b800000, v156
	v_fmamk_f32 v60, v60, 0x3b800000, v156
	v_fmamk_f32 v61, v61, 0x3b800000, v156
	v_rcp_f32_e32 v54, v54
	v_rcp_f32_e32 v55, v55
	v_rcp_f32_e32 v56, v56
	v_rcp_f32_e32 v57, v57
	v_rcp_f32_e32 v50, v50
	v_rcp_f32_e32 v51, v51
	v_rcp_f32_e32 v52, v52
	v_rcp_f32_e32 v53, v53
	v_rcp_f32_e32 v62, v62
	v_rcp_f32_e32 v63, v63
	v_rcp_f32_e32 v64, v64
	v_rcp_f32_e32 v65, v65
	v_rcp_f32_e32 v58, v58
	v_rcp_f32_e32 v59, v59
	v_rcp_f32_e32 v60, v60
	v_rcp_f32_e32 v61, v61
	v_min_f32_e32 v54, v54, v145
	v_min_f32_e32 v55, v55, v145
	v_min_f32_e32 v56, v56, v145
	v_min_f32_e32 v57, v57, v145
	v_min_f32_e32 v50, v50, v145
	v_min_f32_e32 v51, v51, v145
	v_min_f32_e32 v52, v52, v145
	v_min_f32_e32 v53, v53, v145
	v_min_f32_e32 v62, v62, v145
; __device__ __forceinline__ float sigmoidf_(float x) { return frcp(1.0f + fexp2(-x * LOG2E)); }
;   __device__ __forceinline__ void epilogue(int u, f32x4 (&acc)[2][2][4][2]) const {
;     int pm, pn; tile(u, pm, pn);
;     const float* ssq = p->ssq_x + (long)l * NTOK + c * CT + pm * 256;
;     char* grow = (char*)(p->proj + (long)pm * 256 * INW) + 2 * C_MRG + pn * 256;
;     const int t_ = otid(), w_ = t_ >> 6, l_ = t_ & 63, wr = w_ >> 2, wc = w_ & 3, fr = l_ & 15, fq = l_ >> 4;
;     float k256 = 256.f, k255 = 255.f; asm volatile("" : "+v"(k256), "+v"(k255));
; #pragma unroll
;     for (int ai = 0; ai < 2; ++ai)
; #pragma unroll
;       for (int m = 0; m < 4; ++m) {
;         const unsigned r = ai * 128 + wr * 64 + m * 16 + fr;
;         const float rs = rsqrtf(ssq[r] * (1.0f / DM) + EPS) * (1.0f / 32.0f);
; #pragma unroll
;         for (int bj = 0; bj < 2; ++bj) {
;           uint2 gq;
; #pragma unroll
;           for (int n = 0; n < 2; ++n) {
;             const f32x4 v = acc[ai][bj][m][n];
;             const unsigned q0 = (unsigned)fminf(sigmoidf_(v[0] * rs) * k256, k255), q1 = (unsigned)fminf(sigmoidf_(v[1] * rs) * k256, k255);
;             const unsigned q2 = (unsigned)fminf(sigmoidf_(v[2] * rs) * k256, k255), q3 = (unsigned)fminf(sigmoidf_(v[3] * rs) * k256, k255);
;             const unsigned w = q0 | (q1 << 8) | (q2 << 16) | (q3 << 24);
;             if (n == 0) gq.x = w; else gq.y = w;
;           }
;           *(uint2*)(grow + (r * (unsigned)(INW * 2) + (unsigned)(bj * 128 + wc * 32 + fq * 8))) = gq;
;         }
;       }
;   }
	v_min_f32_e32 v63, v63, v145
	v_min_f32_e32 v64, v64, v145
	v_min_f32_e32 v65, v65, v145
	v_min_f32_e32 v58, v58, v145
	v_min_f32_e32 v59, v59, v145
	v_min_f32_e32 v60, v60, v145
	v_min_f32_e32 v61, v61, v145
	v_add_u32_e32 v196, 0x250000, v146
	v_cvt_u32_f32_e32 v176, v54
	v_cvt_u32_f32_e32 v177, v50
	v_cvt_u32_f32_e32 v178, v62
	v_cvt_u32_f32_e32 v179, v58
	v_cvt_u32_f32_sdwa v176, v55 dst_sel:BYTE_1 dst_unused:UNUSED_PRESERVE src0_sel:DWORD
	v_cvt_u32_f32_sdwa v177, v51 dst_sel:BYTE_1 dst_unused:UNUSED_PRESERVE src0_sel:DWORD
	v_cvt_u32_f32_sdwa v178, v63 dst_sel:BYTE_1 dst_unused:UNUSED_PRESERVE src0_sel:DWORD
	v_cvt_u32_f32_sdwa v179, v59 dst_sel:BYTE_1 dst_unused:UNUSED_PRESERVE src0_sel:DWORD
	v_cvt_u32_f32_sdwa v176, v56 dst_sel:BYTE_2 dst_unused:UNUSED_PRESERVE src0_sel:DWORD
	v_cvt_u32_f32_sdwa v177, v52 dst_sel:BYTE_2 dst_unused:UNUSED_PRESERVE src0_sel:DWORD
	v_cvt_u32_f32_sdwa v178, v64 dst_sel:BYTE_2 dst_unused:UNUSED_PRESERVE src0_sel:DWORD
	v_cvt_u32_f32_sdwa v179, v60 dst_sel:BYTE_2 dst_unused:UNUSED_PRESERVE src0_sel:DWORD
	v_cvt_u32_f32_sdwa v176, v57 dst_sel:BYTE_3 dst_unused:UNUSED_PRESERVE src0_sel:DWORD
	v_cvt_u32_f32_sdwa v177, v53 dst_sel:BYTE_3 dst_unused:UNUSED_PRESERVE src0_sel:DWORD
	v_cvt_u32_f32_sdwa v178, v65 dst_sel:BYTE_3 dst_unused:UNUSED_PRESERVE src0_sel:DWORD
	v_cvt_u32_f32_sdwa v179, v61 dst_sel:BYTE_3 dst_unused:UNUSED_PRESERVE src0_sel:DWORD
	s_nop 1
	global_store_dwordx2 v196, v[176:177], s[46:47] offset:128
	global_store_dwordx2 v196, v[178:179], s[46:47]
	v_fmamk_f32 v157, v153, 0x3a800000, v242
	v_mul_f32_e32 v158, 0x4b800000, v157
	v_cmp_gt_f32_e64 s[40:41], s5, v157
	s_nop 1
	v_cndmask_b32_e64 v157, v157, v158, s[40:41]
	v_rsq_f32_e32 v157, v157
	s_nop 0
	v_mul_f32_e32 v158, 0x45800000, v157
	v_cndmask_b32_e64 v157, v157, v158, s[40:41]
	v_mul_f32_e32 v157, 0x3d000000, v157
	v_mul_f32_e32 v157, 0xbfb8aa3b, v157
	v_mul_f32_e32 v38, v38, v157
	v_mul_f32_e32 v39, v39, v157
	v_mul_f32_e32 v40, v40, v157
	v_mul_f32_e32 v41, v41, v157
	v_mul_f32_e32 v34, v34, v157
	v_mul_f32_e32 v35, v35, v157
	v_mul_f32_e32 v36, v36, v157
	v_mul_f32_e32 v37, v37, v157
	v_mul_f32_e32 v46, v46, v157
	v_mul_f32_e32 v47, v47, v157
	v_mul_f32_e32 v48, v48, v157
	v_mul_f32_e32 v49, v49, v157
	v_mul_f32_e32 v42, v42, v157
	v_mul_f32_e32 v43, v43, v157
	v_mul_f32_e32 v44, v44, v157
	v_mul_f32_e32 v45, v45, v157
	v_exp_f32_e32 v38, v38
	v_exp_f32_e32 v39, v39
	v_exp_f32_e32 v40, v40
	v_exp_f32_e32 v41, v41
	v_exp_f32_e32 v34, v34
	v_exp_f32_e32 v35, v35
	v_exp_f32_e32 v36, v36
	v_exp_f32_e32 v37, v37
	v_exp_f32_e32 v46, v46
	v_exp_f32_e32 v47, v47
	v_exp_f32_e32 v48, v48
	v_exp_f32_e32 v49, v49
	v_exp_f32_e32 v42, v42
	v_exp_f32_e32 v43, v43
	v_exp_f32_e32 v44, v44
	v_exp_f32_e32 v45, v45
	v_fmamk_f32 v38, v38, 0x3b800000, v156
	v_fmamk_f32 v39, v39, 0x3b800000, v156
	v_fmamk_f32 v40, v40, 0x3b800000, v156
	v_fmamk_f32 v41, v41, 0x3b800000, v156
	v_fmamk_f32 v34, v34, 0x3b800000, v156
	v_fmamk_f32 v35, v35, 0x3b800000, v156
	v_fmamk_f32 v36, v36, 0x3b800000, v156
	v_fmamk_f32 v37, v37, 0x3b800000, v156
	v_fmamk_f32 v46, v46, 0x3b800000, v156
	v_fmamk_f32 v47, v47, 0x3b800000, v156
	v_fmamk_f32 v48, v48, 0x3b800000, v156
	v_fmamk_f32 v49, v49, 0x3b800000, v156
	v_fmamk_f32 v42, v42, 0x3b800000, v156
	v_fmamk_f32 v43, v43, 0x3b800000, v156
	v_fmamk_f32 v44, v44, 0x3b800000, v156
	v_fmamk_f32 v45, v45, 0x3b800000, v156
	v_rcp_f32_e32 v38, v38
	v_rcp_f32_e32 v39, v39
	v_rcp_f32_e32 v40, v40
	v_rcp_f32_e32 v41, v41
	v_rcp_f32_e32 v34, v34
	v_rcp_f32_e32 v35, v35
	v_rcp_f32_e32 v36, v36
	v_rcp_f32_e32 v37, v37
	v_rcp_f32_e32 v46, v46
	v_rcp_f32_e32 v47, v47
	v_rcp_f32_e32 v48, v48
	v_rcp_f32_e32 v49, v49
	v_rcp_f32_e32 v42, v42
	v_rcp_f32_e32 v43, v43
	v_rcp_f32_e32 v44, v44
	v_rcp_f32_e32 v45, v45
	v_min_f32_e32 v38, v38, v145
	v_min_f32_e32 v39, v39, v145
	v_min_f32_e32 v40, v40, v145
	v_min_f32_e32 v41, v41, v145
	v_min_f32_e32 v34, v34, v145
	v_min_f32_e32 v35, v35, v145
	v_min_f32_e32 v36, v36, v145
	v_min_f32_e32 v37, v37, v145
	v_min_f32_e32 v46, v46, v145
	v_min_f32_e32 v47, v47, v145
	v_min_f32_e32 v48, v48, v145
	v_min_f32_e32 v49, v49, v145
	v_min_f32_e32 v42, v42, v145
	v_min_f32_e32 v43, v43, v145
	v_min_f32_e32 v44, v44, v145
	v_min_f32_e32 v45, v45, v145
	v_add_u32_e32 v197, 0x29a000, v146
	v_cvt_u32_f32_e32 v180, v38
	v_cvt_u32_f32_e32 v181, v34
	v_cvt_u32_f32_e32 v182, v46
	v_cvt_u32_f32_e32 v183, v42
	v_cvt_u32_f32_sdwa v180, v39 dst_sel:BYTE_1 dst_unused:UNUSED_PRESERVE src0_sel:DWORD
	v_cvt_u32_f32_sdwa v181, v35 dst_sel:BYTE_1 dst_unused:UNUSED_PRESERVE src0_sel:DWORD
	v_cvt_u32_f32_sdwa v182, v47 dst_sel:BYTE_1 dst_unused:UNUSED_PRESERVE src0_sel:DWORD
	v_cvt_u32_f32_sdwa v183, v43 dst_sel:BYTE_1 dst_unused:UNUSED_PRESERVE src0_sel:DWORD
	v_cvt_u32_f32_sdwa v180, v40 dst_sel:BYTE_2 dst_unused:UNUSED_PRESERVE src0_sel:DWORD
	v_cvt_u32_f32_sdwa v181, v36 dst_sel:BYTE_2 dst_unused:UNUSED_PRESERVE src0_sel:DWORD
	v_cvt_u32_f32_sdwa v182, v48 dst_sel:BYTE_2 dst_unused:UNUSED_PRESERVE src0_sel:DWORD
	v_cvt_u32_f32_sdwa v183, v44 dst_sel:BYTE_2 dst_unused:UNUSED_PRESERVE src0_sel:DWORD
	v_cvt_u32_f32_sdwa v180, v41 dst_sel:BYTE_3 dst_unused:UNUSED_PRESERVE src0_sel:DWORD
	v_cvt_u32_f32_sdwa v181, v37 dst_sel:BYTE_3 dst_unused:UNUSED_PRESERVE src0_sel:DWORD
	v_cvt_u32_f32_sdwa v182, v49 dst_sel:BYTE_3 dst_unused:UNUSED_PRESERVE src0_sel:DWORD
	v_cvt_u32_f32_sdwa v183, v45 dst_sel:BYTE_3 dst_unused:UNUSED_PRESERVE src0_sel:DWORD
	s_nop 1
	global_store_dwordx2 v197, v[180:181], s[46:47] offset:128
	global_store_dwordx2 v197, v[182:183], s[46:47]
	v_fmamk_f32 v157, v154, 0x3a800000, v242
	v_mul_f32_e32 v158, 0x4b800000, v157
; __device__ __forceinline__ float sigmoidf_(float x) { return frcp(1.0f + fexp2(-x * LOG2E)); }
;   __device__ __forceinline__ void epilogue(int u, f32x4 (&acc)[2][2][4][2]) const {
;     ...
;       for (int m = 0; m < 4; ++m) {
;         const unsigned r = ai * 128 + wr * 64 + m * 16 + fr;
;         const float rs = rsqrtf(ssq[r] * (1.0f / DM) + EPS) * (1.0f / 32.0f);
; #pragma unroll
;         for (int bj = 0; bj < 2; ++bj) {
;           uint2 gq;
; #pragma unroll
;           for (int n = 0; n < 2; ++n) {
;             const f32x4 v = acc[ai][bj][m][n];
;             const unsigned q0 = (unsigned)fminf(sigmoidf_(v[0] * rs) * k256, k255), q1 = (unsigned)fminf(sigmoidf_(v[1] * rs) * k256, k255);
;             const unsigned q2 = (unsigned)fminf(sigmoidf_(v[2] * rs) * k256, k255), q3 = (unsigned)fminf(sigmoidf_(v[3] * rs) * k256, k255);
;             const unsigned w = q0 | (q1 << 8) | (q2 << 16) | (q3 << 24);
;             if (n == 0) gq.x = w; else gq.y = w;
;           }
;           *(uint2*)(grow + (r * (unsigned)(INW * 2) + (unsigned)(bj * 128 + wc * 32 + fq * 8))) = gq;
;         }
	v_cmp_gt_f32_e64 s[40:41], s5, v157
	s_nop 1
	v_cndmask_b32_e64 v157, v157, v158, s[40:41]
	v_rsq_f32_e32 v157, v157
	s_nop 0
	v_mul_f32_e32 v158, 0x45800000, v157
	v_cndmask_b32_e64 v157, v157, v158, s[40:41]
	v_mul_f32_e32 v157, 0x3d000000, v157
	v_mul_f32_e32 v157, 0xbfb8aa3b, v157
	v_mul_f32_e32 v30, v30, v157
	v_mul_f32_e32 v31, v31, v157
	v_mul_f32_e32 v32, v32, v157
	v_mul_f32_e32 v33, v33, v157
	v_mul_f32_e32 v26, v26, v157
	v_mul_f32_e32 v27, v27, v157
	v_mul_f32_e32 v28, v28, v157
	v_mul_f32_e32 v29, v29, v157
	v_mul_f32_e32 v22, v22, v157
	v_mul_f32_e32 v23, v23, v157
	v_mul_f32_e32 v24, v24, v157
	v_mul_f32_e32 v25, v25, v157
	v_mul_f32_e32 v18, v18, v157
	v_mul_f32_e32 v19, v19, v157
	v_mul_f32_e32 v20, v20, v157
	v_mul_f32_e32 v21, v21, v157
	v_exp_f32_e32 v30, v30
	v_exp_f32_e32 v31, v31
	v_exp_f32_e32 v32, v32
	v_exp_f32_e32 v33, v33
	v_exp_f32_e32 v26, v26
	v_exp_f32_e32 v27, v27
	v_exp_f32_e32 v28, v28
	v_exp_f32_e32 v29, v29
	v_exp_f32_e32 v22, v22
	v_exp_f32_e32 v23, v23
	v_exp_f32_e32 v24, v24
	v_exp_f32_e32 v25, v25
	v_exp_f32_e32 v18, v18
	v_exp_f32_e32 v19, v19
	v_exp_f32_e32 v20, v20
	v_exp_f32_e32 v21, v21
	v_fmamk_f32 v30, v30, 0x3b800000, v156
	v_fmamk_f32 v31, v31, 0x3b800000, v156
	v_fmamk_f32 v32, v32, 0x3b800000, v156
	v_fmamk_f32 v33, v33, 0x3b800000, v156
	v_fmamk_f32 v26, v26, 0x3b800000, v156
	v_fmamk_f32 v27, v27, 0x3b800000, v156
	v_fmamk_f32 v28, v28, 0x3b800000, v156
	v_fmamk_f32 v29, v29, 0x3b800000, v156
	v_fmamk_f32 v22, v22, 0x3b800000, v156
	v_fmamk_f32 v23, v23, 0x3b800000, v156
	v_fmamk_f32 v24, v24, 0x3b800000, v156
	v_fmamk_f32 v25, v25, 0x3b800000, v156
	v_fmamk_f32 v18, v18, 0x3b800000, v156
	v_fmamk_f32 v19, v19, 0x3b800000, v156
	v_fmamk_f32 v20, v20, 0x3b800000, v156
	v_fmamk_f32 v21, v21, 0x3b800000, v156
	v_rcp_f32_e32 v30, v30
	v_rcp_f32_e32 v31, v31
	v_rcp_f32_e32 v32, v32
	v_rcp_f32_e32 v33, v33
	v_rcp_f32_e32 v26, v26
	v_rcp_f32_e32 v27, v27
	v_rcp_f32_e32 v28, v28
	v_rcp_f32_e32 v29, v29
	v_rcp_f32_e32 v22, v22
	v_rcp_f32_e32 v23, v23
	v_rcp_f32_e32 v24, v24
	v_rcp_f32_e32 v25, v25
	v_rcp_f32_e32 v18, v18
	v_rcp_f32_e32 v19, v19
	v_rcp_f32_e32 v20, v20
	v_rcp_f32_e32 v21, v21
	v_min_f32_e32 v30, v30, v145
	v_min_f32_e32 v31, v31, v145
	v_min_f32_e32 v32, v32, v145
	v_min_f32_e32 v33, v33, v145
	v_min_f32_e32 v26, v26, v145
	v_min_f32_e32 v27, v27, v145
	v_min_f32_e32 v28, v28, v145
	v_min_f32_e32 v29, v29, v145
	v_min_f32_e32 v22, v22, v145
	v_min_f32_e32 v23, v23, v145
	v_min_f32_e32 v24, v24, v145
	v_min_f32_e32 v25, v25, v145
	v_min_f32_e32 v18, v18, v145
	v_min_f32_e32 v19, v19, v145
	v_min_f32_e32 v20, v20, v145
	v_min_f32_e32 v21, v21, v145
	v_add_u32_e32 v198, 0x2e4000, v146
	v_cvt_u32_f32_e32 v184, v30
	v_cvt_u32_f32_e32 v185, v26
	v_cvt_u32_f32_e32 v186, v22
	v_cvt_u32_f32_e32 v187, v18
	v_cvt_u32_f32_sdwa v184, v31 dst_sel:BYTE_1 dst_unused:UNUSED_PRESERVE src0_sel:DWORD
	v_cvt_u32_f32_sdwa v185, v27 dst_sel:BYTE_1 dst_unused:UNUSED_PRESERVE src0_sel:DWORD
	v_cvt_u32_f32_sdwa v186, v23 dst_sel:BYTE_1 dst_unused:UNUSED_PRESERVE src0_sel:DWORD
	v_cvt_u32_f32_sdwa v187, v19 dst_sel:BYTE_1 dst_unused:UNUSED_PRESERVE src0_sel:DWORD
	v_cvt_u32_f32_sdwa v184, v32 dst_sel:BYTE_2 dst_unused:UNUSED_PRESERVE src0_sel:DWORD
	v_cvt_u32_f32_sdwa v185, v28 dst_sel:BYTE_2 dst_unused:UNUSED_PRESERVE src0_sel:DWORD
	v_cvt_u32_f32_sdwa v186, v24 dst_sel:BYTE_2 dst_unused:UNUSED_PRESERVE src0_sel:DWORD
	v_cvt_u32_f32_sdwa v187, v20 dst_sel:BYTE_2 dst_unused:UNUSED_PRESERVE src0_sel:DWORD
	v_cvt_u32_f32_sdwa v184, v33 dst_sel:BYTE_3 dst_unused:UNUSED_PRESERVE src0_sel:DWORD
	v_cvt_u32_f32_sdwa v185, v29 dst_sel:BYTE_3 dst_unused:UNUSED_PRESERVE src0_sel:DWORD
	v_cvt_u32_f32_sdwa v186, v25 dst_sel:BYTE_3 dst_unused:UNUSED_PRESERVE src0_sel:DWORD
	v_cvt_u32_f32_sdwa v187, v21 dst_sel:BYTE_3 dst_unused:UNUSED_PRESERVE src0_sel:DWORD
	s_nop 1
	global_store_dwordx2 v198, v[184:185], s[46:47]
	global_store_dwordx2 v198, v[186:187], s[46:47] offset:128
	v_fmamk_f32 v157, v155, 0x3a800000, v242
; __device__ __forceinline__ float sigmoidf_(float x) { return frcp(1.0f + fexp2(-x * LOG2E)); }
;   __device__ __forceinline__ void epilogue(int u, f32x4 (&acc)[2][2][4][2]) const {
;     ...
;       for (int m = 0; m < 4; ++m) {
;         const unsigned r = ai * 128 + wr * 64 + m * 16 + fr;
;         const float rs = rsqrtf(ssq[r] * (1.0f / DM) + EPS) * (1.0f / 32.0f);
; #pragma unroll
;         for (int bj = 0; bj < 2; ++bj) {
;           uint2 gq;
; #pragma unroll
;           for (int n = 0; n < 2; ++n) {
;             const f32x4 v = acc[ai][bj][m][n];
;             const unsigned q0 = (unsigned)fminf(sigmoidf_(v[0] * rs) * k256, k255), q1 = (unsigned)fminf(sigmoidf_(v[1] * rs) * k256, k255);
;             const unsigned q2 = (unsigned)fminf(sigmoidf_(v[2] * rs) * k256, k255), q3 = (unsigned)fminf(sigmoidf_(v[3] * rs) * k256, k255);
;             const unsigned w = q0 | (q1 << 8) | (q2 << 16) | (q3 << 24);
;             if (n == 0) gq.x = w; else gq.y = w;
;           }
;           *(uint2*)(grow + (r * (unsigned)(INW * 2) + (unsigned)(bj * 128 + wc * 32 + fq * 8))) = gq;
;         }
	v_mul_f32_e32 v158, 0x4b800000, v157
	v_cmp_gt_f32_e64 s[40:41], s5, v157
	s_nop 1
	v_cndmask_b32_e64 v157, v157, v158, s[40:41]
	v_rsq_f32_e32 v157, v157
	s_nop 0
	v_mul_f32_e32 v158, 0x45800000, v157
	v_cndmask_b32_e64 v157, v157, v158, s[40:41]
	v_mul_f32_e32 v157, 0x3d000000, v157
	v_mul_f32_e32 v157, 0xbfb8aa3b, v157
	v_mul_f32_e32 v14, v14, v157
	v_mul_f32_e32 v15, v15, v157
	v_mul_f32_e32 v16, v16, v157
	v_mul_f32_e32 v17, v17, v157
	v_mul_f32_e32 v10, v10, v157
	v_mul_f32_e32 v11, v11, v157
	v_mul_f32_e32 v12, v12, v157
	v_mul_f32_e32 v13, v13, v157
	v_mul_f32_e32 v6, v6, v157
	v_mul_f32_e32 v7, v7, v157
	v_mul_f32_e32 v8, v8, v157
	v_mul_f32_e32 v9, v9, v157
	v_mul_f32_e32 v2, v2, v157
	v_mul_f32_e32 v3, v3, v157
	v_mul_f32_e32 v4, v4, v157
	v_mul_f32_e32 v5, v5, v157
	v_exp_f32_e32 v14, v14
	v_exp_f32_e32 v15, v15
	v_exp_f32_e32 v16, v16
	v_exp_f32_e32 v17, v17
	v_exp_f32_e32 v10, v10
	v_exp_f32_e32 v11, v11
	v_exp_f32_e32 v12, v12
	v_exp_f32_e32 v13, v13
	v_exp_f32_e32 v6, v6
	v_exp_f32_e32 v7, v7
	v_exp_f32_e32 v8, v8
	v_exp_f32_e32 v9, v9
	v_exp_f32_e32 v2, v2
	v_exp_f32_e32 v3, v3
	v_exp_f32_e32 v4, v4
	v_exp_f32_e32 v5, v5
	v_fmamk_f32 v14, v14, 0x3b800000, v156
	v_fmamk_f32 v15, v15, 0x3b800000, v156
	v_fmamk_f32 v16, v16, 0x3b800000, v156
	v_fmamk_f32 v17, v17, 0x3b800000, v156
	v_fmamk_f32 v10, v10, 0x3b800000, v156
	v_fmamk_f32 v11, v11, 0x3b800000, v156
	v_fmamk_f32 v12, v12, 0x3b800000, v156
	v_fmamk_f32 v13, v13, 0x3b800000, v156
	v_fmamk_f32 v6, v6, 0x3b800000, v156
	v_fmamk_f32 v7, v7, 0x3b800000, v156
	v_fmamk_f32 v8, v8, 0x3b800000, v156
	v_fmamk_f32 v9, v9, 0x3b800000, v156
	v_fmamk_f32 v2, v2, 0x3b800000, v156
	v_fmamk_f32 v3, v3, 0x3b800000, v156
	v_fmamk_f32 v4, v4, 0x3b800000, v156
	v_fmamk_f32 v5, v5, 0x3b800000, v156
	v_rcp_f32_e32 v14, v14
	v_rcp_f32_e32 v15, v15
	v_rcp_f32_e32 v16, v16
	v_rcp_f32_e32 v17, v17
	v_rcp_f32_e32 v10, v10
	v_rcp_f32_e32 v11, v11
	v_rcp_f32_e32 v12, v12
	v_rcp_f32_e32 v13, v13
	v_rcp_f32_e32 v6, v6
	v_rcp_f32_e32 v7, v7
	v_rcp_f32_e32 v8, v8
	v_rcp_f32_e32 v9, v9
	v_rcp_f32_e32 v2, v2
	v_rcp_f32_e32 v3, v3
	v_rcp_f32_e32 v4, v4
	v_rcp_f32_e32 v5, v5
	v_min_f32_e32 v14, v14, v145
	v_min_f32_e32 v15, v15, v145
	v_min_f32_e32 v16, v16, v145
	v_min_f32_e32 v17, v17, v145
	v_min_f32_e32 v10, v10, v145
	v_min_f32_e32 v11, v11, v145
	v_min_f32_e32 v12, v12, v145
	v_min_f32_e32 v13, v13, v145
	v_min_f32_e32 v6, v6, v145
	v_min_f32_e32 v7, v7, v145
	v_min_f32_e32 v8, v8, v145
	v_min_f32_e32 v9, v9, v145
	v_min_f32_e32 v2, v2, v145
	v_min_f32_e32 v3, v3, v145
	v_min_f32_e32 v4, v4, v145
	v_min_f32_e32 v5, v5, v145
	v_add_u32_e32 v199, 0x32e000, v146
	v_cvt_u32_f32_e32 v188, v14
	v_cvt_u32_f32_e32 v189, v10
	v_cvt_u32_f32_e32 v190, v6
	v_cvt_u32_f32_e32 v191, v2
	v_cvt_u32_f32_sdwa v188, v15 dst_sel:BYTE_1 dst_unused:UNUSED_PRESERVE src0_sel:DWORD
	v_cvt_u32_f32_sdwa v189, v11 dst_sel:BYTE_1 dst_unused:UNUSED_PRESERVE src0_sel:DWORD
	v_cvt_u32_f32_sdwa v190, v7 dst_sel:BYTE_1 dst_unused:UNUSED_PRESERVE src0_sel:DWORD
	v_cvt_u32_f32_sdwa v191, v3 dst_sel:BYTE_1 dst_unused:UNUSED_PRESERVE src0_sel:DWORD
	v_cvt_u32_f32_sdwa v188, v16 dst_sel:BYTE_2 dst_unused:UNUSED_PRESERVE src0_sel:DWORD
	v_cvt_u32_f32_sdwa v189, v12 dst_sel:BYTE_2 dst_unused:UNUSED_PRESERVE src0_sel:DWORD
	v_cvt_u32_f32_sdwa v190, v8 dst_sel:BYTE_2 dst_unused:UNUSED_PRESERVE src0_sel:DWORD
	v_cvt_u32_f32_sdwa v191, v4 dst_sel:BYTE_2 dst_unused:UNUSED_PRESERVE src0_sel:DWORD
	v_cvt_u32_f32_sdwa v188, v17 dst_sel:BYTE_3 dst_unused:UNUSED_PRESERVE src0_sel:DWORD
	v_cvt_u32_f32_sdwa v189, v13 dst_sel:BYTE_3 dst_unused:UNUSED_PRESERVE src0_sel:DWORD
	v_cvt_u32_f32_sdwa v190, v9 dst_sel:BYTE_3 dst_unused:UNUSED_PRESERVE src0_sel:DWORD
	v_cvt_u32_f32_sdwa v191, v5 dst_sel:BYTE_3 dst_unused:UNUSED_PRESERVE src0_sel:DWORD
	s_nop 1
	global_store_dwordx2 v199, v[188:189], s[46:47]
	global_store_dwordx2 v199, v[190:191], s[46:47] offset:128
	s_mov_b64 s[46:47], s[44:45]
	s_mov_b64 s[40:41], s[42:43]
	s_cbranch_scc1 .LBB0_350
